# indexer-score loop: 32-key tile copied once per workgroup into LDS by LDS-DMA (waves 0-3, 3 slots, source-side XOR swizzle) and read by all 8 waves with ds_read_b128 behind one barrier per iteration,
# speedup vs baseline: 1.0058x; 1.0058x over previous
; #define BID opqs((int)blockIdx.x)
; DI void score_phase(const Params& p, char* smem) {
;     ...
;   for (int idx = BID; idx < 512; idx += gridDim.x) {
;     const int half = idx & 1, b = (idx >> 1) & 1, t = idx >> 2;
;     const int blk = (t < 64) ? (127 - t) : (t - 64);
;     const int n = (blk + 1) * 64, ntile = n >> 5;
;     const int nt_lo = half ? (ntile >> 1) : 0, nt_hi = half ? ntile : (ntile >> 1);
;     const int t0 = blk * 64 + wave * 8;
;     const u16* Hb = H + (size_t)b * S_ * HLD;
;     bf16x8 af[4][4];
; #pragma unroll
;     for (int rt = 0; rt < 4; ++rt) {
;       const int tokA = t0 + 2 * rt + ((r >> 2) & 1), head = (r >> 3) * 4 + (r & 3);
; #pragma unroll
;       for (int st = 0; st < 4; ++st) af[rt][st] = *(const bf16x8*)(Hb + (size_t)tokA * HLD + 3072 + head * 64 + st * 16 + 8 * h);
;     }
;     wl[lane] = AUX[(size_t)(b * S_ + t0) * 16 + lane] * 0.125f;
;     wl[64 + lane] = AUX[(size_t)(b * S_ + t0) * 16 + 64 + lane] * 0.125f;
;     __syncthreads();
;     float* scb = SC + (size_t)b * SCB + (size_t)2048 * blk * (blk + 1);
;     bf16x8 bfr[4], bnx[4];
; #pragma unroll
;     for (int st = 0; st < 4; ++st) bfr[st] = *(const bf16x8*)(Hb + (size_t)(nt_lo * 32 + r) * HLD + 4096 + st * 16 + 8 * h);
; #pragma unroll 1
;     for (int nt2 = nt_lo; nt2 < nt_hi; ++nt2) {
;       const int k0 = nt2 * 32;
;       const int kn = (nt2 + 1 < nt_hi) ? (k0 + 32) : k0;
; #pragma unroll
;       for (int st = 0; st < 4; ++st) bnx[st] = *(const bf16x8*)(Hb + (size_t)(kn + r) * HLD + 4096 + st * 16 + 8 * h);
.LBB0_819:
	s_waitcnt vmcnt(0)
	v_readlane_b32 s6, v254, 1
	s_add_i32 s10, s10, s6
	s_cmpk_gt_i32 s10, 0x1ff
	s_barrier
	v_readlane_b32 s7, v254, 2
	s_cbranch_scc1 .LBB0_823
.LBB0_820:
	s_ashr_i32 s7, s10, 2
	s_and_b32 s16, s10, 1
	s_bfe_i32 s6, s10, 0x10000
	s_bfe_u32 s8, s10, 0x10001
	s_sub_i32 s9, 0x7f, s7
	s_sub_i32 s15, s7, 64
	s_cmp_lt_i32 s7, 64
	s_cselect_b32 s18, s9, s15
	s_add_i32 s9, s18, 1
	s_and_b32 s15, s6, s9
	s_lshl_b32 s17, s18, 6
	s_mul_i32 s6, s8, 0x5400000
	s_add_u32 s6, s11, s6
	v_add_u32_e32 v2, s17, v198
	s_addc_u32 s7, s12, 0
	v_or_b32_e32 v3, v2, v199
	v_mov_b64_e32 v[4:5], s[6:7]
	s_movk_i32 s22, 0x2a00
	v_mad_i64_i32 v[6:7], s[20:21], v3, s22, v[4:5]
	v_mov_b32_e32 v183, v1
	v_lshl_add_u64 v[6:7], v[6:7], 0, v[182:183]
	v_lshl_add_u64 v[6:7], v[6:7], 0, v[0:1]
	s_mov_b64 s[24:25], 0x1800
	s_movk_i32 s19, 0x1000
	v_lshl_add_u64 v[8:9], v[6:7], 0, s[24:25]
	v_add_co_u32_e32 v6, vcc, s19, v6
	s_lshl_b32 s16, s9, s16
	s_nop 0
	v_addc_co_u32_e32 v7, vcc, 0, v7, vcc
	global_load_dwordx4 v[18:21], v[8:9], off offset:32
	global_load_dwordx4 v[22:25], v[8:9], off offset:64
	global_load_dwordx4 v[26:29], v[6:7], off offset:2048
	global_load_dwordx4 v[30:33], v[8:9], off offset:96
	v_or_b32_e32 v6, 2, v3
	v_mad_i64_i32 v[6:7], s[20:21], v6, s22, v[4:5]
	v_lshl_add_u64 v[6:7], v[6:7], 0, v[182:183]
	v_lshl_add_u64 v[6:7], v[6:7], 0, v[0:1]
	v_lshl_add_u64 v[8:9], v[6:7], 0, s[24:25]
	v_add_co_u32_e32 v6, vcc, s19, v6
	s_cmp_ge_i32 s15, s16
	s_nop 0
	v_addc_co_u32_e32 v7, vcc, 0, v7, vcc
	global_load_dwordx4 v[34:37], v[8:9], off offset:32
	global_load_dwordx4 v[38:41], v[8:9], off offset:64
	global_load_dwordx4 v[42:45], v[6:7], off offset:2048
	global_load_dwordx4 v[46:49], v[8:9], off offset:96
	v_or_b32_e32 v6, 4, v3
	v_mad_i64_i32 v[6:7], s[20:21], v6, s22, v[4:5]
	v_lshl_add_u64 v[6:7], v[6:7], 0, v[182:183]
	v_lshl_add_u64 v[6:7], v[6:7], 0, v[0:1]
	v_lshl_add_u64 v[8:9], v[6:7], 0, s[24:25]
	v_add_co_u32_e32 v6, vcc, s19, v6
	v_or_b32_e32 v3, 6, v3
	s_nop 0
	v_addc_co_u32_e32 v7, vcc, 0, v7, vcc
	global_load_dwordx4 v[50:53], v[8:9], off offset:32
	global_load_dwordx4 v[54:57], v[8:9], off offset:64
	global_load_dwordx4 v[58:61], v[6:7], off offset:2048
	global_load_dwordx4 v[62:65], v[8:9], off offset:96
	v_mad_i64_i32 v[4:5], s[20:21], v3, s22, v[4:5]
	v_lshl_add_u32 v8, s8, 13, v2
	v_lshl_add_u64 v[4:5], v[4:5], 0, v[182:183]
	v_ashrrev_i32_e32 v9, 31, v8
	v_lshl_add_u64 v[4:5], v[4:5], 0, v[0:1]
	v_lshlrev_b64 v[8:9], 6, v[8:9]
	v_lshl_add_u64 v[6:7], v[4:5], 0, s[24:25]
	v_lshl_add_u64 v[8:9], v[180:181], 0, v[8:9]
	v_add_co_u32_e32 v4, vcc, s19, v4
	global_load_dword v3, v[8:9], off
	s_nop 0
	global_load_dword v8, v[8:9], off offset:256
	v_addc_co_u32_e32 v5, vcc, 0, v5, vcc
	global_load_dwordx4 v[66:69], v[6:7], off offset:32
	global_load_dwordx4 v[70:73], v[6:7], off offset:64
	global_load_dwordx4 v[74:77], v[4:5], off offset:2048
	global_load_dwordx4 v[78:81], v[6:7], off offset:96
	s_movk_i32 s23, 0x2000
	s_mov_b64 s[24:25], 0x2000
	s_waitcnt vmcnt(0)
	v_mul_f32_e32 v3, 0x3e000000, v3
	v_mul_f32_e32 v4, 0x3e000000, v8
	ds_write2st64_b32 v200, v3, v4 offset1:1
	s_waitcnt lgkmcnt(0)
	s_barrier
	s_cbranch_scc1 .LBB0_819
	s_mul_i32 s8, s8, 0x8100000
	s_add_u32 s8, s13, s8
	s_mul_hi_i32 s19, s18, s9
	s_mul_i32 s18, s18, s9
	s_addc_u32 s20, s14, 0
	s_lshl_b64 s[18:19], s[18:19], 13
	s_add_u32 s18, s8, s18
	s_addc_u32 s19, s20, s19
	s_lshl_b32 s8, s15, 5
	v_or_b32_e32 v3, s8, v178
	v_mov_b64_e32 v[4:5], s[6:7]
	v_mad_i64_i32 v[4:5], s[20:21], v3, s22, v[4:5]
	v_lshl_add_u64 v[4:5], v[4:5], 0, v[0:1]
	v_lshl_add_u64 v[6:7], v[4:5], 0, s[24:25]
	v_add_co_u32_e32 v4, vcc, s23, v4
	global_load_dwordx4 v[162:165], v[6:7], off offset:96
	s_nop 0
	v_addc_co_u32_e32 v5, vcc, 0, v5, vcc
	global_load_dwordx4 v[174:177], v[4:5], off
	global_load_dwordx4 v[170:173], v[6:7], off offset:32
	global_load_dwordx4 v[166:169], v[6:7], off offset:64
	ds_read_b128 v[82:85], v202
	ds_read_b128 v[86:89], v202 offset:16
	ds_read_b128 v[90:93], v202 offset:32
	ds_read_b128 v[94:97], v202 offset:48
	ds_read_b128 v[98:101], v202 offset:128
	ds_read_b128 v[102:105], v202 offset:144
	ds_read_b128 v[106:109], v202 offset:160
	ds_read_b128 v[110:113], v202 offset:176
	ds_read_b128 v[114:117], v202 offset:256
	ds_read_b128 v[118:121], v202 offset:272
	ds_read_b128 v[122:125], v202 offset:288
	ds_read_b128 v[126:129], v202 offset:304
	ds_read_b128 v[130:133], v202 offset:384
	ds_read_b128 v[134:137], v202 offset:400
	ds_read_b128 v[138:141], v202 offset:416
	ds_read_b128 v[142:145], v202 offset:432
	v_or_b32_e32 v2, v2, v179
	v_subrev_u32_e32 v2, s17, v2
	s_lshl_b32 s9, s9, 6
	v_mov_b32_e32 v185, v1
	v_or_b32_e32 v3, 2, v2
	v_lshl_add_u64 v[186:187], s[18:19], 0, v[184:185]
	v_mad_i64_i32 v[188:189], s[18:19], v2, s9, 0
	v_mad_i64_i32 v[190:191], s[18:19], v3, s9, 0
	v_or_b32_e32 v3, 4, v2
	v_or_b32_e32 v2, 6, v2
	v_mad_i64_i32 v[192:193], s[18:19], v3, s9, 0
	v_mad_i64_i32 v[194:195], s[18:19], v2, s9, 0
	s_add_i32 s19, s8, 32
	s_add_i32 s18, s15, 1
	s_cmp_lt_i32 s18, s16
	s_cselect_b32 s18, s19, s8
	v_and_b32_e32 v240, 63, v201
	v_lshrrev_b32_e32 v241, 6, v201
	s_nop 0
	v_readfirstlane_b32 s32, v241
	v_and_b32_e32 v241, 3, v241
	v_lshrrev_b32_e32 v242, 3, v240
	v_lshl_add_u32 v242, v241, 3, v242
	v_bfe_u32 v243, v242, 1, 3
	v_and_b32_e32 v241, 7, v240
	v_xor_b32_e32 v243, v243, v241
	v_mul_u32_u24_e32 v244, 0x2a00, v242
	v_lshl_add_u32 v244, v243, 4, v244
	s_lshl_b32 s32, s32, 10
	s_add_i32 s32, s32, 0x2000
	v_and_b32_e32 v242, 31, v240
	v_lshrrev_b32_e32 v241, 5, v240
	v_bfe_u32 v243, v242, 1, 3
	v_xor_b32_e32 v243, v243, v241
	v_lshlrev_b32_e32 v242, 7, v242
	v_lshl_add_u32 v246, v243, 4, v242
	v_add_u32_e32 v246, 0x2000, v246
	v_xor_b32_e32 v247, 0x20, v246
	v_xor_b32_e32 v248, 0x40, v246
	v_xor_b32_e32 v249, 0x60, v246
	s_cmp_lt_u32 s32, 0x3000
	s_cbranch_scc0 .Lsc_pre1
	s_mul_i32 s98, s18, 0x2a00
	s_add_u32 s98, s98, s6
	s_addc_u32 s99, s7, 0
	s_add_u32 s98, s98, 0x2000
	s_addc_u32 s99, s99, 0
	s_add_i32 m0, s32, 0x1000
	s_nop 0
	global_load_lds_dwordx4 v244, s[98:99]
; #define MFMA(a, b, c) __builtin_amdgcn_mfma_f32_32x32x16_bf16((a), (b), (c), 0, 0, 0)
; DI void score_phase(const Params& p, char* smem) {
;     ...
;     bf16x8 bfr[4], bnx[4];
; #pragma unroll
;     for (int st = 0; st < 4; ++st) bfr[st] = *(const bf16x8*)(Hb + (size_t)(nt_lo * 32 + r) * HLD + 4096 + st * 16 + 8 * h);
; #pragma unroll 1
;     for (int nt2 = nt_lo; nt2 < nt_hi; ++nt2) {
;       const int k0 = nt2 * 32;
;       const int kn = (nt2 + 1 < nt_hi) ? (k0 + 32) : k0;
; #pragma unroll
;       for (int st = 0; st < 4; ++st) bnx[st] = *(const bf16x8*)(Hb + (size_t)(kn + r) * HLD + 4096 + st * 16 + 8 * h);
; #pragma unroll
;       for (int rt = 0; rt < 4; ++rt) {
;         f32x16 acc;
; #pragma unroll
;         for (int e = 0; e < 16; ++e) acc[e] = 0.f;
; #pragma unroll
;         for (int st = 0; st < 4; ++st) acc = MFMA(af[rt][st], bfr[st], acc);
;         float s = 0.f;
; #pragma unroll
;         for (int e4 = 0; e4 < 4; ++e4) {
;           const f32x4 wv = *(const f32x4*)(wl + (2 * rt + h) * 16 + e4 * 4);
; #pragma unroll
;           for (int i = 0; i < 4; ++i) s += fmaxf(acc[e4 * 4 + i], 0.f) * wv[i];
;         }
;         const int row = (t0 + 2 * rt + h) - blk * 64;
;         __builtin_nontemporal_store(s, scb + (size_t)row * n + k0 + r);
;       }
; #pragma unroll
;       for (int st = 0; st < 4; ++st) bfr[st] = bnx[st];
.Lsc_pre1:
	s_add_i32 s19, s8, 64
	s_add_i32 s18, s15, 2
	s_cmp_lt_i32 s18, s16
	s_cselect_b32 s18, s19, s8
	s_cmp_lt_u32 s32, 0x3000
	s_cbranch_scc0 .Lsc_pre2
	s_mul_i32 s98, s18, 0x2a00
	s_add_u32 s98, s98, s6
	s_addc_u32 s99, s7, 0
	s_add_u32 s98, s98, 0x2000
	s_addc_u32 s99, s99, 0
	s_add_i32 m0, s32, 0x2000
	s_nop 0
	global_load_lds_dwordx4 v244, s[98:99]
.Lsc_pre2:
	s_waitcnt vmcnt(0) lgkmcnt(0)
	v_mfma_f32_32x32x16_bf16 v[2:17], v[26:29], v[174:177], 0
	v_mfma_f32_32x32x16_bf16 v[2:17], v[18:21], v[170:173], v[2:17]
	v_mfma_f32_32x32x16_bf16 v[2:17], v[22:25], v[166:169], v[2:17]
	v_mfma_f32_32x32x16_bf16 v[2:17], v[30:33], v[162:165], v[2:17]
.LBB0_822:
	s_add_i32 s15, s15, 1
	s_add_i32 s17, s8, 32
	s_add_i32 s19, s8, 96
	s_add_i32 s18, s15, 2
	s_cmp_lt_i32 s18, s16
	s_cselect_b32 s18, s19, s8
	s_waitcnt vmcnt(9)
	s_barrier
	s_cmp_lt_u32 s32, 0x3000
	s_cbranch_scc0 .Lsc_nd0
	s_mul_i32 s98, s18, 0x2a00
	s_add_u32 s98, s98, s6
	s_addc_u32 s99, s7, 0
	s_add_u32 s98, s98, 0x2000
	s_addc_u32 s99, s99, 0
	s_add_i32 m0, s32, 0x0
	s_nop 0
	global_load_lds_dwordx4 v244, s[98:99]
.Lsc_nd0:
	ds_read_b128 v[154:157], v246 offset:4096
	ds_read_b128 v[150:153], v247 offset:4096
	ds_read_b128 v[146:149], v248 offset:4096
	ds_read_b128 v[158:161], v249 offset:4096
	s_ashr_i32 s9, s8, 31
	v_lshl_add_u64 v[196:197], s[8:9], 2, v[186:187]
	s_cmp_ge_i32 s15, s16
	s_mov_b32 s8, s17
	v_mfma_f32_32x32x16_bf16 v[224:239], v[42:45], v[174:177], 0
	v_max_f32_e32 v240, 0, v2
	v_fma_f32 v183, v82, v240, 0
	v_max_f32_e32 v241, 0, v3
	v_fmac_f32_e32 v183, v83, v241
	v_max_f32_e32 v240, 0, v4
	v_fmac_f32_e32 v183, v84, v240
	v_max_f32_e32 v241, 0, v5
	v_fmac_f32_e32 v183, v85, v241
	v_mfma_f32_32x32x16_bf16 v[224:239], v[34:37], v[170:173], v[224:239]
	v_max_f32_e32 v240, 0, v6
	v_fmac_f32_e32 v183, v86, v240
	v_max_f32_e32 v241, 0, v7
	v_fmac_f32_e32 v183, v87, v241
	v_max_f32_e32 v240, 0, v8
	v_fmac_f32_e32 v183, v88, v240
	v_max_f32_e32 v241, 0, v9
	v_fmac_f32_e32 v183, v89, v241
	v_mfma_f32_32x32x16_bf16 v[224:239], v[38:41], v[166:169], v[224:239]
	v_max_f32_e32 v240, 0, v10
	v_fmac_f32_e32 v183, v90, v240
	v_max_f32_e32 v241, 0, v11
	v_fmac_f32_e32 v183, v91, v241
	v_max_f32_e32 v240, 0, v12
	v_fmac_f32_e32 v183, v92, v240
	v_max_f32_e32 v241, 0, v13
	v_fmac_f32_e32 v183, v93, v241
	v_mfma_f32_32x32x16_bf16 v[224:239], v[46:49], v[162:165], v[224:239]
	v_max_f32_e32 v240, 0, v14
	v_fmac_f32_e32 v183, v94, v240
	v_max_f32_e32 v241, 0, v15
	v_fmac_f32_e32 v183, v95, v241
	v_max_f32_e32 v240, 0, v16
	v_fmac_f32_e32 v183, v96, v240
	v_max_f32_e32 v241, 0, v17
	v_fmac_f32_e32 v183, v97, v241
	v_lshl_add_u64 v[242:243], v[188:189], 2, v[196:197]
	global_store_dword v[242:243], v183, off nt
	s_nop 1
	v_mfma_f32_32x32x16_bf16 v[2:17], v[58:61], v[174:177], 0
	v_max_f32_e32 v240, 0, v224
	v_fma_f32 v183, v98, v240, 0
	v_max_f32_e32 v241, 0, v225
	v_fmac_f32_e32 v183, v99, v241
	v_max_f32_e32 v240, 0, v226
	v_fmac_f32_e32 v183, v100, v240
	v_max_f32_e32 v241, 0, v227
	v_fmac_f32_e32 v183, v101, v241
	v_mfma_f32_32x32x16_bf16 v[2:17], v[50:53], v[170:173], v[2:17]
	v_max_f32_e32 v240, 0, v228
	v_fmac_f32_e32 v183, v102, v240
	v_max_f32_e32 v241, 0, v229
	v_fmac_f32_e32 v183, v103, v241
	v_max_f32_e32 v240, 0, v230
	v_fmac_f32_e32 v183, v104, v240
	v_max_f32_e32 v241, 0, v231
	v_fmac_f32_e32 v183, v105, v241
	v_mfma_f32_32x32x16_bf16 v[2:17], v[54:57], v[166:169], v[2:17]
	v_max_f32_e32 v240, 0, v232
	v_fmac_f32_e32 v183, v106, v240
	v_max_f32_e32 v241, 0, v233
	v_fmac_f32_e32 v183, v107, v241
	v_max_f32_e32 v240, 0, v234
	v_fmac_f32_e32 v183, v108, v240
	v_max_f32_e32 v241, 0, v235
	v_fmac_f32_e32 v183, v109, v241
	v_mfma_f32_32x32x16_bf16 v[2:17], v[62:65], v[162:165], v[2:17]
	v_max_f32_e32 v240, 0, v236
	v_fmac_f32_e32 v183, v110, v240
	v_max_f32_e32 v241, 0, v237
	v_fmac_f32_e32 v183, v111, v241
	v_max_f32_e32 v240, 0, v238
	v_fmac_f32_e32 v183, v112, v240
	v_max_f32_e32 v241, 0, v239
	v_fmac_f32_e32 v183, v113, v241
	v_lshl_add_u64 v[242:243], v[190:191], 2, v[196:197]
	global_store_dword v[242:243], v183, off nt
	s_nop 1
	v_mfma_f32_32x32x16_bf16 v[224:239], v[74:77], v[174:177], 0
	v_max_f32_e32 v240, 0, v2
	v_fma_f32 v183, v114, v240, 0
	v_max_f32_e32 v241, 0, v3
	v_fmac_f32_e32 v183, v115, v241
	v_max_f32_e32 v240, 0, v4
	v_fmac_f32_e32 v183, v116, v240
	v_max_f32_e32 v241, 0, v5
	v_fmac_f32_e32 v183, v117, v241
	v_mfma_f32_32x32x16_bf16 v[224:239], v[66:69], v[170:173], v[224:239]
	v_max_f32_e32 v240, 0, v6
	v_fmac_f32_e32 v183, v118, v240
	v_max_f32_e32 v241, 0, v7
	v_fmac_f32_e32 v183, v119, v241
	v_max_f32_e32 v240, 0, v8
	v_fmac_f32_e32 v183, v120, v240
	v_max_f32_e32 v241, 0, v9
	v_fmac_f32_e32 v183, v121, v241
	v_mfma_f32_32x32x16_bf16 v[224:239], v[70:73], v[166:169], v[224:239]
	v_max_f32_e32 v240, 0, v10
	v_fmac_f32_e32 v183, v122, v240
	v_max_f32_e32 v241, 0, v11
	v_fmac_f32_e32 v183, v123, v241
	v_max_f32_e32 v240, 0, v12
	v_fmac_f32_e32 v183, v124, v240
	v_max_f32_e32 v241, 0, v13
	v_fmac_f32_e32 v183, v125, v241
	v_mfma_f32_32x32x16_bf16 v[224:239], v[78:81], v[162:165], v[224:239]
	v_max_f32_e32 v240, 0, v14
	v_fmac_f32_e32 v183, v126, v240
	v_max_f32_e32 v241, 0, v15
	v_fmac_f32_e32 v183, v127, v241
	v_max_f32_e32 v240, 0, v16
	v_fmac_f32_e32 v183, v128, v240
	v_max_f32_e32 v241, 0, v17
	v_fmac_f32_e32 v183, v129, v241
	v_lshl_add_u64 v[242:243], v[192:193], 2, v[196:197]
	global_store_dword v[242:243], v183, off nt
	s_nop 1
	s_waitcnt lgkmcnt(0)
	v_mfma_f32_32x32x16_bf16 v[2:17], v[26:29], v[154:157], 0
	v_max_f32_e32 v240, 0, v224
	v_fma_f32 v183, v130, v240, 0
	v_max_f32_e32 v241, 0, v225
	v_fmac_f32_e32 v183, v131, v241
	v_max_f32_e32 v240, 0, v226
	v_fmac_f32_e32 v183, v132, v240
	v_max_f32_e32 v241, 0, v227
	v_fmac_f32_e32 v183, v133, v241
	v_mfma_f32_32x32x16_bf16 v[2:17], v[18:21], v[150:153], v[2:17]
	v_max_f32_e32 v240, 0, v228
	v_fmac_f32_e32 v183, v134, v240
	v_max_f32_e32 v241, 0, v229
	v_fmac_f32_e32 v183, v135, v241
	v_max_f32_e32 v240, 0, v230
	v_fmac_f32_e32 v183, v136, v240
	v_max_f32_e32 v241, 0, v231
	v_fmac_f32_e32 v183, v137, v241
	v_mfma_f32_32x32x16_bf16 v[2:17], v[22:25], v[146:149], v[2:17]
	v_max_f32_e32 v240, 0, v232
	v_fmac_f32_e32 v183, v138, v240
	v_max_f32_e32 v241, 0, v233
	v_fmac_f32_e32 v183, v139, v241
	v_max_f32_e32 v240, 0, v234
	v_fmac_f32_e32 v183, v140, v240
	v_max_f32_e32 v241, 0, v235
	v_fmac_f32_e32 v183, v141, v241
	v_mfma_f32_32x32x16_bf16 v[2:17], v[30:33], v[158:161], v[2:17]
	v_max_f32_e32 v240, 0, v236
	v_fmac_f32_e32 v183, v142, v240
	v_max_f32_e32 v241, 0, v237
	v_fmac_f32_e32 v183, v143, v241
	v_max_f32_e32 v240, 0, v238
	v_fmac_f32_e32 v183, v144, v240
	v_max_f32_e32 v241, 0, v239
	v_fmac_f32_e32 v183, v145, v241
	v_lshl_add_u64 v[242:243], v[194:195], 2, v[196:197]
	global_store_dword v[242:243], v183, off nt
	s_nop 1
	s_cbranch_scc1 .LBB0_819
; #define MFMA(a, b, c) __builtin_amdgcn_mfma_f32_32x32x16_bf16((a), (b), (c), 0, 0, 0)
; DI void score_phase(const Params& p, char* smem) {
;     ...
;     for (int nt2 = nt_lo; nt2 < nt_hi; ++nt2) {
;       const int k0 = nt2 * 32;
;       const int kn = (nt2 + 1 < nt_hi) ? (k0 + 32) : k0;
; #pragma unroll
;       for (int st = 0; st < 4; ++st) bnx[st] = *(const bf16x8*)(Hb + (size_t)(kn + r) * HLD + 4096 + st * 16 + 8 * h);
; #pragma unroll
;       for (int rt = 0; rt < 4; ++rt) {
;         f32x16 acc;
; #pragma unroll
;         for (int e = 0; e < 16; ++e) acc[e] = 0.f;
; #pragma unroll
;         for (int st = 0; st < 4; ++st) acc = MFMA(af[rt][st], bfr[st], acc);
;         float s = 0.f;
; #pragma unroll
;         for (int e4 = 0; e4 < 4; ++e4) {
;           const f32x4 wv = *(const f32x4*)(wl + (2 * rt + h) * 16 + e4 * 4);
; #pragma unroll
;           for (int i = 0; i < 4; ++i) s += fmaxf(acc[e4 * 4 + i], 0.f) * wv[i];
;         }
;         const int row = (t0 + 2 * rt + h) - blk * 64;
;         __builtin_nontemporal_store(s, scb + (size_t)row * n + k0 + r);
;       }
; #pragma unroll
;       for (int st = 0; st < 4; ++st) bfr[st] = bnx[st];
	s_add_i32 s15, s15, 1
	s_add_i32 s17, s8, 32
	s_add_i32 s19, s8, 96
	s_add_i32 s18, s15, 2
	s_cmp_lt_i32 s18, s16
	s_cselect_b32 s18, s19, s8
	s_waitcnt vmcnt(9)
	s_barrier
	s_cmp_lt_u32 s32, 0x3000
	s_cbranch_scc0 .Lsc_nd1
	s_mul_i32 s98, s18, 0x2a00
	s_add_u32 s98, s98, s6
	s_addc_u32 s99, s7, 0
	s_add_u32 s98, s98, 0x2000
	s_addc_u32 s99, s99, 0
	s_add_i32 m0, s32, 0x1000
	s_nop 0
	global_load_lds_dwordx4 v244, s[98:99]
.Lsc_nd1:
	ds_read_b128 v[204:207], v246 offset:8192
	ds_read_b128 v[208:211], v247 offset:8192
	ds_read_b128 v[212:215], v248 offset:8192
	ds_read_b128 v[250:253], v249 offset:8192
	s_ashr_i32 s9, s8, 31
	v_lshl_add_u64 v[196:197], s[8:9], 2, v[186:187]
	s_cmp_ge_i32 s15, s16
	s_mov_b32 s8, s17
	v_mfma_f32_32x32x16_bf16 v[224:239], v[42:45], v[154:157], 0
	v_max_f32_e32 v240, 0, v2
	v_fma_f32 v183, v82, v240, 0
	v_max_f32_e32 v241, 0, v3
	v_fmac_f32_e32 v183, v83, v241
	v_max_f32_e32 v240, 0, v4
	v_fmac_f32_e32 v183, v84, v240
	v_max_f32_e32 v241, 0, v5
	v_fmac_f32_e32 v183, v85, v241
	v_mfma_f32_32x32x16_bf16 v[224:239], v[34:37], v[150:153], v[224:239]
	v_max_f32_e32 v240, 0, v6
	v_fmac_f32_e32 v183, v86, v240
	v_max_f32_e32 v241, 0, v7
	v_fmac_f32_e32 v183, v87, v241
	v_max_f32_e32 v240, 0, v8
	v_fmac_f32_e32 v183, v88, v240
	v_max_f32_e32 v241, 0, v9
	v_fmac_f32_e32 v183, v89, v241
	v_mfma_f32_32x32x16_bf16 v[224:239], v[38:41], v[146:149], v[224:239]
	v_max_f32_e32 v240, 0, v10
	v_fmac_f32_e32 v183, v90, v240
	v_max_f32_e32 v241, 0, v11
	v_fmac_f32_e32 v183, v91, v241
	v_max_f32_e32 v240, 0, v12
	v_fmac_f32_e32 v183, v92, v240
	v_max_f32_e32 v241, 0, v13
	v_fmac_f32_e32 v183, v93, v241
	v_mfma_f32_32x32x16_bf16 v[224:239], v[46:49], v[158:161], v[224:239]
	v_max_f32_e32 v240, 0, v14
	v_fmac_f32_e32 v183, v94, v240
	v_max_f32_e32 v241, 0, v15
	v_fmac_f32_e32 v183, v95, v241
	v_max_f32_e32 v240, 0, v16
	v_fmac_f32_e32 v183, v96, v240
	v_max_f32_e32 v241, 0, v17
	v_fmac_f32_e32 v183, v97, v241
	v_lshl_add_u64 v[242:243], v[188:189], 2, v[196:197]
	global_store_dword v[242:243], v183, off nt
	s_nop 1
	v_mfma_f32_32x32x16_bf16 v[2:17], v[58:61], v[154:157], 0
	v_max_f32_e32 v240, 0, v224
	v_fma_f32 v183, v98, v240, 0
	v_max_f32_e32 v241, 0, v225
	v_fmac_f32_e32 v183, v99, v241
	v_max_f32_e32 v240, 0, v226
	v_fmac_f32_e32 v183, v100, v240
	v_max_f32_e32 v241, 0, v227
	v_fmac_f32_e32 v183, v101, v241
	v_mfma_f32_32x32x16_bf16 v[2:17], v[50:53], v[150:153], v[2:17]
	v_max_f32_e32 v240, 0, v228
	v_fmac_f32_e32 v183, v102, v240
	v_max_f32_e32 v241, 0, v229
	v_fmac_f32_e32 v183, v103, v241
	v_max_f32_e32 v240, 0, v230
	v_fmac_f32_e32 v183, v104, v240
	v_max_f32_e32 v241, 0, v231
	v_fmac_f32_e32 v183, v105, v241
	v_mfma_f32_32x32x16_bf16 v[2:17], v[54:57], v[146:149], v[2:17]
	v_max_f32_e32 v240, 0, v232
	v_fmac_f32_e32 v183, v106, v240
	v_max_f32_e32 v241, 0, v233
	v_fmac_f32_e32 v183, v107, v241
	v_max_f32_e32 v240, 0, v234
	v_fmac_f32_e32 v183, v108, v240
	v_max_f32_e32 v241, 0, v235
	v_fmac_f32_e32 v183, v109, v241
	v_mfma_f32_32x32x16_bf16 v[2:17], v[62:65], v[158:161], v[2:17]
	v_max_f32_e32 v240, 0, v236
	v_fmac_f32_e32 v183, v110, v240
	v_max_f32_e32 v241, 0, v237
	v_fmac_f32_e32 v183, v111, v241
	v_max_f32_e32 v240, 0, v238
	v_fmac_f32_e32 v183, v112, v240
	v_max_f32_e32 v241, 0, v239
	v_fmac_f32_e32 v183, v113, v241
	v_lshl_add_u64 v[242:243], v[190:191], 2, v[196:197]
	global_store_dword v[242:243], v183, off nt
	s_nop 1
	v_mfma_f32_32x32x16_bf16 v[224:239], v[74:77], v[154:157], 0
	v_max_f32_e32 v240, 0, v2
	v_fma_f32 v183, v114, v240, 0
	v_max_f32_e32 v241, 0, v3
	v_fmac_f32_e32 v183, v115, v241
	v_max_f32_e32 v240, 0, v4
	v_fmac_f32_e32 v183, v116, v240
	v_max_f32_e32 v241, 0, v5
	v_fmac_f32_e32 v183, v117, v241
	v_mfma_f32_32x32x16_bf16 v[224:239], v[66:69], v[150:153], v[224:239]
	v_max_f32_e32 v240, 0, v6
	v_fmac_f32_e32 v183, v118, v240
	v_max_f32_e32 v241, 0, v7
	v_fmac_f32_e32 v183, v119, v241
	v_max_f32_e32 v240, 0, v8
	v_fmac_f32_e32 v183, v120, v240
	v_max_f32_e32 v241, 0, v9
	v_fmac_f32_e32 v183, v121, v241
	v_mfma_f32_32x32x16_bf16 v[224:239], v[70:73], v[146:149], v[224:239]
	v_max_f32_e32 v240, 0, v10
	v_fmac_f32_e32 v183, v122, v240
	v_max_f32_e32 v241, 0, v11
	v_fmac_f32_e32 v183, v123, v241
	v_max_f32_e32 v240, 0, v12
	v_fmac_f32_e32 v183, v124, v240
	v_max_f32_e32 v241, 0, v13
	v_fmac_f32_e32 v183, v125, v241
	v_mfma_f32_32x32x16_bf16 v[224:239], v[78:81], v[158:161], v[224:239]
	v_max_f32_e32 v240, 0, v14
	v_fmac_f32_e32 v183, v126, v240
	v_max_f32_e32 v241, 0, v15
	v_fmac_f32_e32 v183, v127, v241
	v_max_f32_e32 v240, 0, v16
	v_fmac_f32_e32 v183, v128, v240
	v_max_f32_e32 v241, 0, v17
	v_fmac_f32_e32 v183, v129, v241
	v_lshl_add_u64 v[242:243], v[192:193], 2, v[196:197]
	global_store_dword v[242:243], v183, off nt
	s_nop 1
	s_waitcnt lgkmcnt(0)
	v_mfma_f32_32x32x16_bf16 v[2:17], v[26:29], v[204:207], 0
	v_max_f32_e32 v240, 0, v224
	v_fma_f32 v183, v130, v240, 0
	v_max_f32_e32 v241, 0, v225
	v_fmac_f32_e32 v183, v131, v241
	v_max_f32_e32 v240, 0, v226
	v_fmac_f32_e32 v183, v132, v240
	v_max_f32_e32 v241, 0, v227
	v_fmac_f32_e32 v183, v133, v241
	v_mfma_f32_32x32x16_bf16 v[2:17], v[18:21], v[208:211], v[2:17]
	v_max_f32_e32 v240, 0, v228
	v_fmac_f32_e32 v183, v134, v240
	v_max_f32_e32 v241, 0, v229
	v_fmac_f32_e32 v183, v135, v241
	v_max_f32_e32 v240, 0, v230
	v_fmac_f32_e32 v183, v136, v240
	v_max_f32_e32 v241, 0, v231
	v_fmac_f32_e32 v183, v137, v241
	v_mfma_f32_32x32x16_bf16 v[2:17], v[22:25], v[212:215], v[2:17]
	v_max_f32_e32 v240, 0, v232
	v_fmac_f32_e32 v183, v138, v240
	v_max_f32_e32 v241, 0, v233
	v_fmac_f32_e32 v183, v139, v241
	v_max_f32_e32 v240, 0, v234
	v_fmac_f32_e32 v183, v140, v240
	v_max_f32_e32 v241, 0, v235
	v_fmac_f32_e32 v183, v141, v241
	v_mfma_f32_32x32x16_bf16 v[2:17], v[30:33], v[250:253], v[2:17]
	v_max_f32_e32 v240, 0, v236
	v_fmac_f32_e32 v183, v142, v240
	v_max_f32_e32 v241, 0, v237
	v_fmac_f32_e32 v183, v143, v241
	v_max_f32_e32 v240, 0, v238
	v_fmac_f32_e32 v183, v144, v240
	v_max_f32_e32 v241, 0, v239
	v_fmac_f32_e32 v183, v145, v241
	v_lshl_add_u64 v[242:243], v[194:195], 2, v[196:197]
	global_store_dword v[242:243], v183, off nt
	s_nop 1
	s_cbranch_scc1 .LBB0_819
	s_add_i32 s15, s15, 1
	s_add_i32 s17, s8, 32
	s_add_i32 s19, s8, 96
	s_add_i32 s18, s15, 2
	s_cmp_lt_i32 s18, s16
	s_cselect_b32 s18, s19, s8
	s_waitcnt vmcnt(9)
	s_barrier
	s_cmp_lt_u32 s32, 0x3000
	s_cbranch_scc0 .Lsc_nd2
	s_mul_i32 s98, s18, 0x2a00
	s_add_u32 s98, s98, s6
	s_addc_u32 s99, s7, 0
	s_add_u32 s98, s98, 0x2000
	s_addc_u32 s99, s99, 0
	s_add_i32 m0, s32, 0x2000
	s_nop 0
	global_load_lds_dwordx4 v244, s[98:99]
; #define MFMA(a, b, c) __builtin_amdgcn_mfma_f32_32x32x16_bf16((a), (b), (c), 0, 0, 0)
; DI void score_phase(const Params& p, char* smem) {
;     ...
;     for (int nt2 = nt_lo; nt2 < nt_hi; ++nt2) {
;       const int k0 = nt2 * 32;
;       const int kn = (nt2 + 1 < nt_hi) ? (k0 + 32) : k0;
; #pragma unroll
;       for (int st = 0; st < 4; ++st) bnx[st] = *(const bf16x8*)(Hb + (size_t)(kn + r) * HLD + 4096 + st * 16 + 8 * h);
; #pragma unroll
;       for (int rt = 0; rt < 4; ++rt) {
;         f32x16 acc;
; #pragma unroll
;         for (int e = 0; e < 16; ++e) acc[e] = 0.f;
; #pragma unroll
;         for (int st = 0; st < 4; ++st) acc = MFMA(af[rt][st], bfr[st], acc);
;         float s = 0.f;
; #pragma unroll
;         for (int e4 = 0; e4 < 4; ++e4) {
;           const f32x4 wv = *(const f32x4*)(wl + (2 * rt + h) * 16 + e4 * 4);
; #pragma unroll
;           for (int i = 0; i < 4; ++i) s += fmaxf(acc[e4 * 4 + i], 0.f) * wv[i];
;         }
;         const int row = (t0 + 2 * rt + h) - blk * 64;
;         __builtin_nontemporal_store(s, scb + (size_t)row * n + k0 + r);
;       }
; #pragma unroll
;       for (int st = 0; st < 4; ++st) bfr[st] = bnx[st];
.Lsc_nd2:
	ds_read_b128 v[174:177], v246 offset:0
	ds_read_b128 v[170:173], v247 offset:0
	ds_read_b128 v[166:169], v248 offset:0
	ds_read_b128 v[162:165], v249 offset:0
	s_ashr_i32 s9, s8, 31
	v_lshl_add_u64 v[196:197], s[8:9], 2, v[186:187]
	s_cmp_ge_i32 s15, s16
	s_mov_b32 s8, s17
	v_mfma_f32_32x32x16_bf16 v[224:239], v[42:45], v[204:207], 0
	v_max_f32_e32 v240, 0, v2
	v_fma_f32 v183, v82, v240, 0
	v_max_f32_e32 v241, 0, v3
	v_fmac_f32_e32 v183, v83, v241
	v_max_f32_e32 v240, 0, v4
	v_fmac_f32_e32 v183, v84, v240
	v_max_f32_e32 v241, 0, v5
	v_fmac_f32_e32 v183, v85, v241
	v_mfma_f32_32x32x16_bf16 v[224:239], v[34:37], v[208:211], v[224:239]
	v_max_f32_e32 v240, 0, v6
	v_fmac_f32_e32 v183, v86, v240
	v_max_f32_e32 v241, 0, v7
	v_fmac_f32_e32 v183, v87, v241
	v_max_f32_e32 v240, 0, v8
	v_fmac_f32_e32 v183, v88, v240
	v_max_f32_e32 v241, 0, v9
	v_fmac_f32_e32 v183, v89, v241
	v_mfma_f32_32x32x16_bf16 v[224:239], v[38:41], v[212:215], v[224:239]
	v_max_f32_e32 v240, 0, v10
	v_fmac_f32_e32 v183, v90, v240
	v_max_f32_e32 v241, 0, v11
	v_fmac_f32_e32 v183, v91, v241
	v_max_f32_e32 v240, 0, v12
	v_fmac_f32_e32 v183, v92, v240
	v_max_f32_e32 v241, 0, v13
	v_fmac_f32_e32 v183, v93, v241
	v_mfma_f32_32x32x16_bf16 v[224:239], v[46:49], v[250:253], v[224:239]
	v_max_f32_e32 v240, 0, v14
	v_fmac_f32_e32 v183, v94, v240
	v_max_f32_e32 v241, 0, v15
	v_fmac_f32_e32 v183, v95, v241
	v_max_f32_e32 v240, 0, v16
	v_fmac_f32_e32 v183, v96, v240
	v_max_f32_e32 v241, 0, v17
	v_fmac_f32_e32 v183, v97, v241
	v_lshl_add_u64 v[242:243], v[188:189], 2, v[196:197]
	global_store_dword v[242:243], v183, off nt
	s_nop 1
	v_mfma_f32_32x32x16_bf16 v[2:17], v[58:61], v[204:207], 0
	v_max_f32_e32 v240, 0, v224
	v_fma_f32 v183, v98, v240, 0
	v_max_f32_e32 v241, 0, v225
	v_fmac_f32_e32 v183, v99, v241
	v_max_f32_e32 v240, 0, v226
	v_fmac_f32_e32 v183, v100, v240
	v_max_f32_e32 v241, 0, v227
	v_fmac_f32_e32 v183, v101, v241
	v_mfma_f32_32x32x16_bf16 v[2:17], v[50:53], v[208:211], v[2:17]
	v_max_f32_e32 v240, 0, v228
	v_fmac_f32_e32 v183, v102, v240
	v_max_f32_e32 v241, 0, v229
	v_fmac_f32_e32 v183, v103, v241
	v_max_f32_e32 v240, 0, v230
	v_fmac_f32_e32 v183, v104, v240
	v_max_f32_e32 v241, 0, v231
	v_fmac_f32_e32 v183, v105, v241
	v_mfma_f32_32x32x16_bf16 v[2:17], v[54:57], v[212:215], v[2:17]
	v_max_f32_e32 v240, 0, v232
	v_fmac_f32_e32 v183, v106, v240
	v_max_f32_e32 v241, 0, v233
	v_fmac_f32_e32 v183, v107, v241
	v_max_f32_e32 v240, 0, v234
	v_fmac_f32_e32 v183, v108, v240
	v_max_f32_e32 v241, 0, v235
	v_fmac_f32_e32 v183, v109, v241
	v_mfma_f32_32x32x16_bf16 v[2:17], v[62:65], v[250:253], v[2:17]
	v_max_f32_e32 v240, 0, v236
	v_fmac_f32_e32 v183, v110, v240
	v_max_f32_e32 v241, 0, v237
	v_fmac_f32_e32 v183, v111, v241
	v_max_f32_e32 v240, 0, v238
	v_fmac_f32_e32 v183, v112, v240
	v_max_f32_e32 v241, 0, v239
	v_fmac_f32_e32 v183, v113, v241
	v_lshl_add_u64 v[242:243], v[190:191], 2, v[196:197]
	global_store_dword v[242:243], v183, off nt
	s_nop 1
	v_mfma_f32_32x32x16_bf16 v[224:239], v[74:77], v[204:207], 0
	v_max_f32_e32 v240, 0, v2
	v_fma_f32 v183, v114, v240, 0
	v_max_f32_e32 v241, 0, v3
	v_fmac_f32_e32 v183, v115, v241
	v_max_f32_e32 v240, 0, v4
	v_fmac_f32_e32 v183, v116, v240
	v_max_f32_e32 v241, 0, v5
	v_fmac_f32_e32 v183, v117, v241
	v_mfma_f32_32x32x16_bf16 v[224:239], v[66:69], v[208:211], v[224:239]
	v_max_f32_e32 v240, 0, v6
	v_fmac_f32_e32 v183, v118, v240
	v_max_f32_e32 v241, 0, v7
	v_fmac_f32_e32 v183, v119, v241
	v_max_f32_e32 v240, 0, v8
	v_fmac_f32_e32 v183, v120, v240
	v_max_f32_e32 v241, 0, v9
	v_fmac_f32_e32 v183, v121, v241
	v_mfma_f32_32x32x16_bf16 v[224:239], v[70:73], v[212:215], v[224:239]
	v_max_f32_e32 v240, 0, v10
	v_fmac_f32_e32 v183, v122, v240
	v_max_f32_e32 v241, 0, v11
	v_fmac_f32_e32 v183, v123, v241
	v_max_f32_e32 v240, 0, v12
	v_fmac_f32_e32 v183, v124, v240
	v_max_f32_e32 v241, 0, v13
	v_fmac_f32_e32 v183, v125, v241
	v_mfma_f32_32x32x16_bf16 v[224:239], v[78:81], v[250:253], v[224:239]
	v_max_f32_e32 v240, 0, v14
	v_fmac_f32_e32 v183, v126, v240
	v_max_f32_e32 v241, 0, v15
	v_fmac_f32_e32 v183, v127, v241
	v_max_f32_e32 v240, 0, v16
	v_fmac_f32_e32 v183, v128, v240
	v_max_f32_e32 v241, 0, v17
	v_fmac_f32_e32 v183, v129, v241
	v_lshl_add_u64 v[242:243], v[192:193], 2, v[196:197]
	global_store_dword v[242:243], v183, off nt
	s_nop 1
	s_waitcnt lgkmcnt(0)
	v_mfma_f32_32x32x16_bf16 v[2:17], v[26:29], v[174:177], 0
	v_max_f32_e32 v240, 0, v224
	v_fma_f32 v183, v130, v240, 0
	v_max_f32_e32 v241, 0, v225
	v_fmac_f32_e32 v183, v131, v241
	v_max_f32_e32 v240, 0, v226
	v_fmac_f32_e32 v183, v132, v240
	v_max_f32_e32 v241, 0, v227
	v_fmac_f32_e32 v183, v133, v241
	v_mfma_f32_32x32x16_bf16 v[2:17], v[18:21], v[170:173], v[2:17]
	v_max_f32_e32 v240, 0, v228
	v_fmac_f32_e32 v183, v134, v240
	v_max_f32_e32 v241, 0, v229
	v_fmac_f32_e32 v183, v135, v241
	v_max_f32_e32 v240, 0, v230
	v_fmac_f32_e32 v183, v136, v240
	v_max_f32_e32 v241, 0, v231
	v_fmac_f32_e32 v183, v137, v241
	v_mfma_f32_32x32x16_bf16 v[2:17], v[22:25], v[166:169], v[2:17]
	v_max_f32_e32 v240, 0, v232
	v_fmac_f32_e32 v183, v138, v240
	v_max_f32_e32 v241, 0, v233
	v_fmac_f32_e32 v183, v139, v241
	v_max_f32_e32 v240, 0, v234
	v_fmac_f32_e32 v183, v140, v240
	v_max_f32_e32 v241, 0, v235
	v_fmac_f32_e32 v183, v141, v241
	v_mfma_f32_32x32x16_bf16 v[2:17], v[30:33], v[162:165], v[2:17]
	v_max_f32_e32 v240, 0, v236
	v_fmac_f32_e32 v183, v142, v240
	v_max_f32_e32 v241, 0, v237
	v_fmac_f32_e32 v183, v143, v241
	v_max_f32_e32 v240, 0, v238
	v_fmac_f32_e32 v183, v144, v240
	v_max_f32_e32 v241, 0, v239
	v_fmac_f32_e32 v183, v145, v241
	v_lshl_add_u64 v[242:243], v[194:195], 2, v[196:197]
	global_store_dword v[242:243], v183, off nt
	s_nop 1
	s_cbranch_scc0 .LBB0_822
	s_branch .LBB0_819
